# ffn_down prologue: a thread finishes both fix-up rows of its columns (conv weights and the two shared raw rows loaded once, all 14 loads in flight)
# speedup vs baseline: 1.0085x; 1.0061x over previous
; DI unsigned pk2(float lo, float hi) { f32x2 v = {lo, hi}; bf16x2_t b = __builtin_convertvector(v, bf16x2_t); return __builtin_bit_cast(unsigned, b); }
; DI float siluf_(float x) { return x * frcp(1.f + __expf(-x)); }
; DI void ffn_fix_tile(const Ctx& c, const float* cw, int pm) {
;     if ((pm & 7) == 0) return;
;     const float* RAWB = (const float*)(c.ws + WS_RAWB);
;     for (int idx = c.tid; idx < 2 * 1408; idx += 512) {
;         const int r = idx / 1408, c4 = idx - r * 1408, col = 4 * c4;
;         const float* cur_t = RAWB + ((size_t)pm * 4 + r) * 11264;
;         const float* p1_t = r == 0 ? RAWB + ((size_t)(pm - 1) * 4 + 3) * 11264 : RAWB + ((size_t)pm * 4 + 0) * 11264;
;         const float* p2_t = r == 0 ? RAWB + ((size_t)(pm - 1) * 4 + 2) * 11264 : RAWB + ((size_t)(pm - 1) * 4 + 3) * 11264;
;         f32x4 ug = *(const f32x4*)(cw + col) * *(const f32x4*)(p2_t + col) + *(const f32x4*)(cw + 11264 + col) * *(const f32x4*)(p1_t + col) + *(const f32x4*)(cw + 2 * 11264 + col) * *(const f32x4*)(cur_t + col);
;         f32x4 uv = *(const f32x4*)(cw + 5632 + col) * *(const f32x4*)(p2_t + 5632 + col) + *(const f32x4*)(cw + 11264 + 5632 + col) * *(const f32x4*)(p1_t + 5632 + col) + *(const f32x4*)(cw + 2 * 11264 + 5632 + col) * *(const f32x4*)(cur_t + 5632 + col);
;         u32x2 o; o.x = pk2(siluf_(ug.x) * uv.x, siluf_(ug.y) * uv.y); o.y = pk2(siluf_(ug.z) * uv.z, siluf_(ug.w) * uv.w);
;         *(u32x2*)(c.ACT + ((size_t)pm * 256 + r) * DFF + col) = o;
;     }
; }
.LBB0_2017:
	s_ashr_i32 s28, s34, 3
	s_add_i32 s28, s39, s28
	s_ashr_i32 s29, s28, 31
	s_lshr_b32 s29, s29, 27
	s_add_i32 s29, s28, s29
	s_ashr_i32 s34, s29, 5
	s_lshl_b32 s34, s34, 2
	s_sub_i32 s35, 64, s34
	s_min_i32 s35, s35, 4
	s_abs_i32 s35, s35
	v_cvt_f32_u32_e32 v0, s35
	s_sub_i32 s39, 0, s35
	s_andn2_b32 s29, s29, 31
	s_sub_i32 s28, s28, s29
	v_rcp_iflag_f32_e32 v0, v0
	s_ashr_i32 s29, s28, 31
	s_abs_i32 s28, s28
	v_mul_f32_e32 v0, 0x4f7ffffe, v0
	v_cvt_u32_f32_e32 v0, v0
	s_nop 0
	v_readfirstlane_b32 s40, v0
	s_mul_i32 s39, s39, s40
	s_mul_hi_u32 s39, s40, s39
	s_add_i32 s40, s40, s39
	s_mul_hi_u32 s39, s28, s40
	s_mul_i32 s39, s39, s35
	s_sub_i32 s28, s28, s39
	s_sub_i32 s39, s28, s35
	s_cmp_ge_u32 s28, s35
	s_cselect_b32 s28, s39, s28
	s_sub_i32 s39, s28, s35
	s_cmp_ge_u32 s28, s35
	s_cselect_b32 s28, s39, s28
	s_xor_b32 s28, s28, s29
	s_sub_i32 s28, s28, s29
	s_add_i32 s28, s34, s28
	s_cmp_lg_u32 s28, s38
	s_cbranch_scc0 .LBB0_2010
	s_and_b32 s29, s28, 7
	s_cmp_lg_u32 s29, 0
	s_cselect_b64 s[34:35], -1, 0
	s_and_b64 s[38:39], s[34:35], s[26:27]
	s_and_saveexec_b64 s[34:35], s[38:39]
	s_cbranch_execz .LBB0_2009
	s_ashr_i32 s29, s28, 31
	s_lshl_b64 s[40:41], s[28:29], 2
	s_mul_i32 s39, s28, 0x2c000
	s_mul_hi_i32 s38, s28, 0x2c000
	s_add_u32 s29, s24, s39
	s_addc_u32 s38, s25, s38
	s_add_i32 s42, s28, -1
	s_add_i32 s39, s39, 0xfffd4000
	s_mul_hi_i32 s42, s42, 0x2c000
	s_add_u32 s43, s24, s39
	s_addc_u32 s42, s25, s42
	s_add_u32 s39, s43, 0x21000
	s_addc_u32 s44, s42, 0
	s_add_u32 s45, s43, 0x16000
	s_addc_u32 s46, s42, 0
	s_mul_hi_i32 s43, s28, 0xfc
	s_mul_i32 s42, s28, 0xfc
	s_mov_b64 s[72:73], 0
	s_mul_i32 s90, s28, 0x2c0000
	s_add_u32 s90, s14, s90
	s_addc_u32 s91, s15, 0
	s_mov_b32 s92, 0xb000
	s_mov_b32 s93, 0
	s_mov_b32 s94, s87
	s_mov_b32 s95, 0
	s_mov_b32 s96, 0x2c00
	s_mov_b32 s97, 0
	v_mov_b32_e32 v5, v4
.Lffnfix_loop:
	v_lshlrev_b32_e32 v0, 2, v5
	v_mov_b32_e32 v1, 0
	v_lshlrev_b64 v[24:25], 2, v[0:1]
	v_mov_b32_e32 v6, s45
	v_mov_b32_e32 v7, s46
	v_lshl_add_u64 v[26:27], v[6:7], 0, v[24:25]
	v_mov_b32_e32 v6, s39
	v_mov_b32_e32 v7, s44
	v_lshl_add_u64 v[28:29], v[6:7], 0, v[24:25]
	v_mov_b32_e32 v6, s29
	v_mov_b32_e32 v7, s38
	v_lshl_add_u64 v[22:23], v[6:7], 0, v[24:25]
	v_lshl_add_u64 v[20:21], v[22:23], 0, s[92:93]
	v_lshl_add_u64 v[6:7], s[8:9], 0, v[24:25]
	global_load_dwordx4 v[40:43], v[6:7], off
	v_lshl_add_u64 v[6:7], s[10:11], 0, v[24:25]
	global_load_dwordx4 v[44:47], v[6:7], off
	v_lshl_add_u64 v[6:7], s[16:17], 0, v[24:25]
	global_load_dwordx4 v[48:51], v[6:7], off
	global_load_dwordx4 v[52:55], v[26:27], off
	global_load_dwordx4 v[56:59], v[28:29], off
	global_load_dwordx4 v[60:63], v[22:23], off
	global_load_dwordx4 v[64:67], v[20:21], off
	v_lshl_add_u64 v[6:7], s[18:19], 0, v[24:25]
	global_load_dwordx4 v[68:71], v[6:7], off
	v_lshl_add_u64 v[6:7], s[20:21], 0, v[24:25]
	global_load_dwordx4 v[72:75], v[6:7], off
	v_lshl_add_u64 v[6:7], s[22:23], 0, v[24:25]
	global_load_dwordx4 v[76:79], v[6:7], off
	v_lshl_add_u64 v[34:35], v[26:27], 0, s[94:95]
	global_load_dwordx4 v[80:83], v[34:35], off offset:2048
	v_lshl_add_u64 v[34:35], v[28:29], 0, s[94:95]
	global_load_dwordx4 v[84:87], v[34:35], off offset:2048
	v_lshl_add_u64 v[34:35], v[22:23], 0, s[94:95]
	global_load_dwordx4 v[88:91], v[34:35], off offset:2048
	v_lshl_add_u64 v[34:35], v[20:21], 0, s[94:95]
	global_load_dwordx4 v[92:95], v[34:35], off offset:2048
	s_waitcnt vmcnt(7)
	v_pk_mul_f32 v[14:15], v[44:45], v[56:57]
	v_pk_mul_f32 v[16:17], v[46:47], v[58:59]
	v_pk_fma_f32 v[14:15], v[40:41], v[52:53], v[14:15]
	v_pk_fma_f32 v[16:17], v[42:43], v[54:55], v[16:17]
	v_pk_fma_f32 v[96:97], v[48:49], v[60:61], v[14:15]
	v_pk_fma_f32 v[98:99], v[50:51], v[62:63], v[16:17]
	v_pk_mul_f32 v[14:15], v[44:45], v[60:61]
	v_pk_mul_f32 v[16:17], v[46:47], v[62:63]
	v_pk_fma_f32 v[14:15], v[40:41], v[56:57], v[14:15]
	v_pk_fma_f32 v[16:17], v[42:43], v[58:59], v[16:17]
	v_pk_fma_f32 v[100:101], v[48:49], v[64:65], v[14:15]
	v_pk_fma_f32 v[102:103], v[50:51], v[66:67], v[16:17]
	s_waitcnt vmcnt(0)
	v_pk_mul_f32 v[14:15], v[72:73], v[84:85]
	v_pk_mul_f32 v[16:17], v[74:75], v[86:87]
	v_pk_fma_f32 v[14:15], v[68:69], v[80:81], v[14:15]
	v_pk_fma_f32 v[16:17], v[70:71], v[82:83], v[16:17]
	v_pk_fma_f32 v[104:105], v[76:77], v[88:89], v[14:15]
	v_pk_fma_f32 v[106:107], v[78:79], v[90:91], v[16:17]
	v_pk_mul_f32 v[14:15], v[72:73], v[88:89]
	v_pk_mul_f32 v[16:17], v[74:75], v[90:91]
	v_pk_fma_f32 v[14:15], v[68:69], v[84:85], v[14:15]
	v_pk_fma_f32 v[16:17], v[70:71], v[86:87], v[16:17]
	v_pk_fma_f32 v[108:109], v[76:77], v[92:93], v[14:15]
	v_pk_fma_f32 v[110:111], v[78:79], v[94:95], v[16:17]
	v_mul_f32_e32 v10, 0xbfb8aa3b, v96
	v_mul_f32_e32 v11, 0xbfb8aa3b, v97
	v_exp_f32_e32 v10, v10
	v_exp_f32_e32 v11, v11
	s_nop 0
	v_add_f32_e32 v10, 1.0, v10
	v_add_f32_e32 v11, 1.0, v11
	v_rcp_f32_e32 v10, v10
	v_rcp_f32_e32 v11, v11
	s_nop 0
	v_pk_mul_f32 v[10:11], v[96:97], v[10:11]
	s_nop 0
	v_pk_mul_f32 v[12:13], v[10:11], v[104:105]
	s_nop 0
	v_cvt_pk_bf16_f32 v112, v12, v13
	v_mul_f32_e32 v10, 0xbfb8aa3b, v98
	v_mul_f32_e32 v11, 0xbfb8aa3b, v99
	v_exp_f32_e32 v10, v10
	v_exp_f32_e32 v11, v11
	s_nop 0
	v_add_f32_e32 v10, 1.0, v10
	v_add_f32_e32 v11, 1.0, v11
	v_rcp_f32_e32 v10, v10
	v_rcp_f32_e32 v11, v11
	s_nop 0
	v_pk_mul_f32 v[10:11], v[98:99], v[10:11]
	s_nop 0
	v_pk_mul_f32 v[12:13], v[10:11], v[106:107]
	s_nop 0
	v_cvt_pk_bf16_f32 v113, v12, v13
	v_mul_f32_e32 v10, 0xbfb8aa3b, v100
	v_mul_f32_e32 v11, 0xbfb8aa3b, v101
	v_exp_f32_e32 v10, v10
	v_exp_f32_e32 v11, v11
	s_nop 0
	v_add_f32_e32 v10, 1.0, v10
	v_add_f32_e32 v11, 1.0, v11
	v_rcp_f32_e32 v10, v10
	v_rcp_f32_e32 v11, v11
	s_nop 0
	v_pk_mul_f32 v[10:11], v[100:101], v[10:11]
	s_nop 0
	v_pk_mul_f32 v[12:13], v[10:11], v[108:109]
	s_nop 0
	v_cvt_pk_bf16_f32 v114, v12, v13
	v_mul_f32_e32 v10, 0xbfb8aa3b, v102
	v_mul_f32_e32 v11, 0xbfb8aa3b, v103
	v_exp_f32_e32 v10, v10
	v_exp_f32_e32 v11, v11
	s_nop 0
	v_add_f32_e32 v10, 1.0, v10
	v_add_f32_e32 v11, 1.0, v11
	v_rcp_f32_e32 v10, v10
	v_rcp_f32_e32 v11, v11
	s_nop 0
	v_pk_mul_f32 v[10:11], v[102:103], v[10:11]
	s_nop 0
	v_pk_mul_f32 v[12:13], v[10:11], v[110:111]
	s_nop 0
	v_cvt_pk_bf16_f32 v115, v12, v13
	v_lshl_add_u64 v[34:35], v[0:1], 1, s[90:91]
	v_lshl_add_u64 v[36:37], v[34:35], 0, s[96:97]
	global_store_dwordx2 v[34:35], v[112:113], off
	global_store_dwordx2 v[36:37], v[114:115], off
	v_add_u32_e32 v5, 0x200, v5
	v_cmp_gt_u32_e32 vcc, 0x580, v5
	s_and_b64 exec, exec, vcc
	s_cbranch_execnz .Lffnfix_loop
	s_branch .LBB0_2009
